# attention DMA blocks without m0 save/restore, no pad nops between max3 ops, on top of no-setprio + P4 rework
# baseline (speedup 1.0000x reference)
.LBB0_342:
	s_or_b64 exec, exec, s[52:53]
	s_bfe_u32 s14, s73, 0x10003
	s_ashr_i32 s15, s0, 6
	s_lshl_b32 s81, s14, 7
	s_lshl_b32 s80, s15, 4
	s_add_i32 s80, s80, s81
	s_lshl_b64 s[0:1], s[4:5], 11
	s_lshl_b32 s58, s69, 8
	s_or_b32 s0, s0, s58
	s_ashr_i32 s46, s80, 31
	s_add_u32 s0, s0, s80
	s_addc_u32 s1, s1, s46
	s_lshl_b64 s[0:1], s[0:1], 8
	v_and_b32_e32 v17, 15, v16
	s_add_u32 s0, s28, s0
	s_addc_u32 s1, s29, s1
	v_lshlrev_b32_e32 v96, 8, v17
	v_lshl_add_u64 v[0:1], s[0:1], 0, v[96:97]
	v_and_b32_e32 v96, 48, v16
	s_waitcnt vmcnt(8)
	v_lshl_add_u64 v[12:13], v[0:1], 0, v[96:97]
	global_load_dwordx4 v[0:3], v[12:13], off nt
	global_load_dwordx4 v[4:7], v[12:13], off offset:64 nt
	global_load_dwordx4 v[8:11], v[12:13], off offset:128 nt
	s_nop 0
	global_load_dwordx4 v[12:15], v[12:13], off offset:192 nt
	s_lshl_b64 s[0:1], s[4:5], 19
	s_add_u32 s82, s8, s0
	s_addc_u32 s84, s9, s1
	s_add_u32 s85, s16, s0
	s_addc_u32 s86, s17, s1
	s_lshl_b32 s0, s15, 3
	s_lshl_b32 s1, s15, 1
	s_or_b32 s4, s0, 4
	v_bfe_u32 v50, v16, 4, 2
	s_lshl_b32 s46, s69, 2
	s_and_b32 s1, s1, 2
	s_bfe_u32 s5, s4, 0x20002
	s_cmp_eq_u32 s14, 0
	v_or_b32_e32 v18, s0, v50
	v_bitop3_b32 v19, s0, v16, v50 bitop3:0x36
	s_cselect_b64 s[56:57], -1, 0
	v_lshlrev_b32_e32 v107, 2, v50
	v_lshlrev_b32_e32 v18, 8, v18
	v_lshlrev_b32_e32 v19, 4, v19
	v_and_or_b32 v96, v19, s70, v18
	v_bitop3_b32 v19, s1, v17, v107 bitop3:0x36
	s_and_b64 s[0:1], s[56:57], exec
	s_cselect_b32 s87, 2, 4
	s_lshl_b32 s88, s15, 11
	v_lshl_or_b32 v98, v19, 4, v18
	v_or_b32_e32 v18, s4, v50
	v_bitop3_b32 v19, s4, v16, v50 bitop3:0x36
	s_lshl_b32 s0, s69, 16
	s_add_i32 s88, s88, 0
	v_lshlrev_b32_e32 v18, 8, v18
	v_lshlrev_b32_e32 v19, 4, v19
	s_add_u32 s4, s82, s0
	v_and_or_b32 v100, v19, s70, v18
	v_bitop3_b32 v19, s5, v17, v107 bitop3:0x36
	s_addc_u32 s5, s84, 0
	s_add_u32 s14, s85, s0
	v_lshl_or_b32 v102, v19, 4, v18
	s_addc_u32 s15, s86, 0
	s_add_i32 s1, s88, 0x4000
	v_lshl_add_u64 v[18:19], s[4:5], 0, v[96:97]
	s_mov_b32 m0, s88
	s_nop 0
	global_load_lds_dwordx4 v[18:19], off
	v_mov_b32_e32 v99, v97
	v_lshl_add_u64 v[18:19], s[14:15], 0, v[98:99]
	s_mov_b32 m0, s1
	s_nop 0
	global_load_lds_dwordx4 v[18:19], off
	v_mov_b32_e32 v101, v97
	s_add_i32 s1, s88, 0x400
	v_lshl_add_u64 v[18:19], s[4:5], 0, v[100:101]
	s_mov_b32 m0, s1
	s_nop 0
	global_load_lds_dwordx4 v[18:19], off
	v_mov_b32_e32 v103, v97
	s_add_i32 s1, s88, 0x4400
	v_lshl_add_u64 v[18:19], s[14:15], 0, v[102:103]
	s_mov_b32 m0, s1
	s_nop 0
	global_load_lds_dwordx4 v[18:19], off
	s_or_b32 s1, s0, 0x4000
	s_add_i32 s52, s88, 0x8000
	s_add_u32 s4, s82, s1
	s_addc_u32 s5, s84, 0
	s_add_u32 s14, s85, s1
	s_addc_u32 s15, s86, 0
	v_lshl_add_u64 v[18:19], s[4:5], 0, v[96:97]
	s_mov_b32 m0, s52
	s_nop 0
	global_load_lds_dwordx4 v[18:19], off
	s_add_i32 s1, s88, 0xc000
	v_lshl_add_u64 v[18:19], s[14:15], 0, v[98:99]
	s_mov_b32 m0, s1
	s_nop 0
	global_load_lds_dwordx4 v[18:19], off
	v_lshl_add_u64 v[18:19], s[4:5], 0, v[100:101]
	s_add_i32 s1, s88, 0x8400
	s_mov_b32 m0, s1
	s_nop 0
	global_load_lds_dwordx4 v[18:19], off
	v_lshl_add_u64 v[18:19], s[14:15], 0, v[102:103]
	s_add_i32 s1, s88, 0xc400
	s_mov_b32 m0, s1
	s_nop 0
	global_load_lds_dwordx4 v[18:19], off
	s_add_i32 s89, s87, s46
	s_cmp_gt_u32 s89, 2
	s_cbranch_scc0 .LBB0_344
	s_or_b32 s4, s0, 0x8000
	s_and_b64 s[0:1], s[56:57], exec
	s_cselect_b32 s4, 0, s4
	s_add_i32 s14, s88, 0x10000
	s_add_u32 s0, s82, s4
	s_addc_u32 s1, s84, 0
	s_add_u32 s4, s85, s4
	s_addc_u32 s5, s86, 0
	v_lshl_add_u64 v[18:19], s[0:1], 0, v[96:97]
	s_mov_b32 m0, s14
	s_nop 0
	global_load_lds_dwordx4 v[18:19], off
	s_add_i32 s15, s88, 0x14000
	v_lshl_add_u64 v[18:19], s[4:5], 0, v[98:99]
	s_mov_b32 m0, s15
	s_nop 0
	global_load_lds_dwordx4 v[18:19], off
	v_lshl_add_u64 v[18:19], s[0:1], 0, v[100:101]
	s_add_i32 s0, s88, 0x10400
	s_mov_b32 m0, s0
	s_nop 0
	global_load_lds_dwordx4 v[18:19], off
	v_lshl_add_u64 v[18:19], s[4:5], 0, v[102:103]
	s_add_i32 s0, s88, 0x14400
	s_mov_b32 m0, s0
	s_nop 0
	global_load_lds_dwordx4 v[18:19], off

.LBB0_371:
	s_andn2_b64 vcc, exec, s[4:5]
	s_cbranch_vccnz .LBB0_373
	s_add_i32 s0, s93, s95
	s_add_i32 s4, s0, 3
	s_lshr_b32 s5, s4, 2
	s_and_b32 s4, s4, 3
	s_cmp_lt_u32 s1, s87
	s_cselect_b32 s5, s69, s5
	s_cselect_b32 s1, s1, s4
	s_lshl_b32 s4, s5, 8
	s_lshl_b32 s1, s1, 6
	s_add_i32 s46, s4, s1
	s_add_i32 s1, s90, 0x18000
	s_and_b32 s1, s1, 0x18000
	s_lshl_b64 s[4:5], s[46:47], 8
	s_add_i32 s1, s88, s1
	s_add_u32 s14, s82, s4
	s_addc_u32 s15, s84, s5
	s_add_u32 s4, s85, s4
	s_addc_u32 s5, s86, s5
	v_lshl_add_u64 v[48:49], s[14:15], 0, v[96:97]
	s_mov_b32 m0, s1
	s_nop 0
	global_load_lds_dwordx4 v[48:49], off
	s_add_i32 s46, s1, 0x4000
	v_lshl_add_u64 v[48:49], s[4:5], 0, v[98:99]
	s_mov_b32 m0, s46
	s_nop 0
	global_load_lds_dwordx4 v[48:49], off
	v_lshl_add_u64 v[48:49], s[14:15], 0, v[100:101]
	s_add_i32 s14, s1, 0x400
	s_mov_b32 m0, s14
	s_nop 0
	global_load_lds_dwordx4 v[48:49], off
	v_lshl_add_u64 v[48:49], s[4:5], 0, v[102:103]
	s_addk_i32 s1, 0x4400
	s_mov_b32 m0, s1
	s_nop 0
	global_load_lds_dwordx4 v[48:49], off

.LBB0_381:
	v_max3_f32 v134, v92, v93, v94
	s_nop 5
	v_max_f32_e32 v135, v83, v83
	v_max3_f32 v134, v134, v95, v88
	s_or_b64 s[4:5], s[60:61], s[4:5]
	v_max3_f32 v134, v134, v89, v90
	v_max3_f32 v134, v134, v91, v84
	v_max3_f32 v134, v134, v85, v86
	v_max3_f32 v134, v134, v87, v80
	v_max3_f32 v134, v134, v81, v82
	s_nop 0
	v_max_f32_e32 v134, v134, v134
	v_max_f32_e32 v134, v134, v135
	v_cndmask_b32_e64 v134, v106, v134, s[4:5]
	ds_swizzle_b32 v135, v134 offset:swizzle(SWAP,16)
	s_waitcnt lgkmcnt(0)
	v_max_f32_e32 v135, v135, v135
	v_max_f32_e32 v134, v134, v135
	ds_bpermute_b32 v135, v105, v134
	s_waitcnt lgkmcnt(0)
	v_max_f32_e32 v135, v135, v135
	v_max_f32_e32 v134, v134, v135
	v_mul_f32_e32 v134, 0x3e0293ee, v134
	v_add_f32_e32 v135, 0x41000000, v108
	v_cmp_gt_f32_e32 vcc, v134, v135
	s_cbranch_vccz .LBB0_359
	v_max_f32_e32 v134, v134, v134
	v_max_f32_e32 v135, v108, v108
	v_max_f32_e32 v134, v135, v134
	v_sub_f32_e32 v108, v108, v134
	v_exp_f32_e32 v108, v108
	s_nop 0
	v_pk_mul_f32 v[42:43], v[42:43], v[108:109] op_sel_hi:[1,0]
	v_pk_mul_f32 v[40:41], v[40:41], v[108:109] op_sel_hi:[1,0]
	v_pk_mul_f32 v[46:47], v[46:47], v[108:109] op_sel_hi:[1,0]
	v_pk_mul_f32 v[44:45], v[44:45], v[108:109] op_sel_hi:[1,0]
	v_pk_mul_f32 v[38:39], v[38:39], v[108:109] op_sel_hi:[1,0]
	v_pk_mul_f32 v[36:37], v[36:37], v[108:109] op_sel_hi:[1,0]
	v_pk_mul_f32 v[34:35], v[34:35], v[108:109] op_sel_hi:[1,0]
	v_pk_mul_f32 v[32:33], v[32:33], v[108:109] op_sel_hi:[1,0]
	v_pk_mul_f32 v[30:31], v[30:31], v[108:109] op_sel_hi:[1,0]
	v_pk_mul_f32 v[28:29], v[28:29], v[108:109] op_sel_hi:[1,0]
	v_pk_mul_f32 v[26:27], v[26:27], v[108:109] op_sel_hi:[1,0]
	v_pk_mul_f32 v[24:25], v[24:25], v[108:109] op_sel_hi:[1,0]
	v_pk_mul_f32 v[22:23], v[22:23], v[108:109] op_sel_hi:[1,0]
	v_pk_mul_f32 v[20:21], v[20:21], v[108:109] op_sel_hi:[1,0]
	v_pk_mul_f32 v[18:19], v[18:19], v[108:109] op_sel_hi:[1,0]
	v_pk_mul_f32 v[16:17], v[16:17], v[108:109] op_sel_hi:[1,0]
	v_mul_f32_e32 v124, v124, v108
	v_mov_b32_e32 v108, v134
	s_branch .LBB0_359

.LBB0_396:
	s_or_b64 exec, exec, s[4:5]
	s_ashr_i32 s4, s0, 6
	s_xor_b32 s0, s81, 0x80
	s_lshl_b32 s64, s4, 4
	s_add_i32 s64, s64, s0
	s_lshl_b64 s[0:1], s[58:59], 11
	s_lshl_b32 s60, s80, 8
	s_or_b32 s0, s0, s60
	s_ashr_i32 s5, s64, 31
	s_add_u32 s0, s0, s64
	s_addc_u32 s1, s1, s5
	s_lshl_b64 s[0:1], s[0:1], 8
	v_and_b32_e32 v17, 15, v16
	s_add_u32 s0, s28, s0
	s_addc_u32 s1, s29, s1
	v_lshlrev_b32_e32 v96, 8, v17
	v_lshl_add_u64 v[0:1], s[0:1], 0, v[96:97]
	v_and_b32_e32 v96, 48, v16
	v_lshl_add_u64 v[12:13], v[0:1], 0, v[96:97]
	global_load_dwordx4 v[0:3], v[12:13], off nt
	global_load_dwordx4 v[4:7], v[12:13], off offset:64 nt
	global_load_dwordx4 v[8:11], v[12:13], off offset:128 nt
	s_nop 0
	global_load_dwordx4 v[12:15], v[12:13], off offset:192 nt
	s_lshl_b64 s[0:1], s[58:59], 19
	s_add_u32 s59, s8, s0
	s_addc_u32 s65, s9, s1
	s_add_u32 s66, s16, s0
	v_bfe_u32 v18, v16, 4, 2
	s_addc_u32 s67, s17, s1
	s_lshl_b32 s0, s4, 3
	v_or_b32_e32 v19, s0, v18
	v_bitop3_b32 v20, s0, v16, v18 bitop3:0x36
	s_lshl_b32 s1, s4, 1
	v_lshlrev_b32_e32 v107, 2, v18
	v_lshlrev_b32_e32 v19, 8, v19
	v_lshlrev_b32_e32 v20, 4, v20
	s_and_b32 s1, s1, 2
	v_and_or_b32 v96, v20, s70, v19
	v_bitop3_b32 v20, s1, v17, v107 bitop3:0x36
	s_or_b32 s0, s0, 4
	v_lshl_or_b32 v98, v20, 4, v19
	v_or_b32_e32 v19, s0, v18
	v_bitop3_b32 v20, s0, v16, v18 bitop3:0x36
	s_lshl_b32 s46, s80, 2
	v_lshlrev_b32_e32 v19, 8, v19
	v_lshlrev_b32_e32 v20, 4, v20
	s_bfe_u32 s0, s0, 0x20002
	v_and_or_b32 v100, v20, s70, v19
	v_bitop3_b32 v20, s0, v17, v107 bitop3:0x36
	s_and_b64 s[0:1], s[56:57], exec
	s_cselect_b32 s68, 4, 2
	s_lshl_b32 s69, s4, 11
	s_lshl_b32 s0, s80, 16
	s_add_i32 s69, s69, 0
	s_add_u32 s4, s59, s0
	s_addc_u32 s5, s65, 0
	s_add_u32 s14, s66, s0
	v_lshl_or_b32 v102, v20, 4, v19
	s_addc_u32 s15, s67, 0
	s_add_i32 s1, s69, 0x4000
	v_lshl_add_u64 v[20:21], s[4:5], 0, v[96:97]
	s_mov_b32 m0, s69
	s_nop 0
	global_load_lds_dwordx4 v[20:21], off
	v_mov_b32_e32 v99, v97
	v_lshl_add_u64 v[20:21], s[14:15], 0, v[98:99]
	s_mov_b32 m0, s1
	s_nop 0
	global_load_lds_dwordx4 v[20:21], off
	v_mov_b32_e32 v101, v97
	s_add_i32 s1, s69, 0x400
	v_lshl_add_u64 v[20:21], s[4:5], 0, v[100:101]
	s_mov_b32 m0, s1
	s_nop 0
	global_load_lds_dwordx4 v[20:21], off
	v_mov_b32_e32 v103, v97
	s_add_i32 s1, s69, 0x4400
	v_lshl_add_u64 v[20:21], s[14:15], 0, v[102:103]
	s_mov_b32 m0, s1
	s_nop 0
	global_load_lds_dwordx4 v[20:21], off
	s_or_b32 s1, s0, 0x4000
	s_add_i32 s61, s69, 0x8000
	s_add_u32 s4, s59, s1
	s_addc_u32 s5, s65, 0
	s_add_u32 s14, s66, s1
	s_addc_u32 s15, s67, 0
	v_lshl_add_u64 v[20:21], s[4:5], 0, v[96:97]
	s_mov_b32 m0, s61
	s_nop 0
	global_load_lds_dwordx4 v[20:21], off
	s_add_i32 s1, s69, 0xc000
	v_lshl_add_u64 v[20:21], s[14:15], 0, v[98:99]
	s_mov_b32 m0, s1
	s_nop 0
	global_load_lds_dwordx4 v[20:21], off
	v_lshl_add_u64 v[20:21], s[4:5], 0, v[100:101]
	s_add_i32 s1, s69, 0x8400
	s_mov_b32 m0, s1
	s_nop 0
	global_load_lds_dwordx4 v[20:21], off
	v_lshl_add_u64 v[20:21], s[14:15], 0, v[102:103]
	s_add_i32 s1, s69, 0xc400
	s_mov_b32 m0, s1
	s_nop 0
	global_load_lds_dwordx4 v[20:21], off
	s_add_i32 s75, s68, s46
	s_cmp_gt_u32 s75, 2
	s_cbranch_scc0 .LBB0_398
	s_or_b32 s4, s0, 0x8000
	s_and_b64 s[0:1], s[56:57], exec
	s_cselect_b32 s4, s4, 0
	s_add_i32 s14, s69, 0x10000
	s_add_u32 s0, s59, s4
	s_addc_u32 s1, s65, 0
	s_add_u32 s4, s66, s4
	s_addc_u32 s5, s67, 0
	v_lshl_add_u64 v[20:21], s[0:1], 0, v[96:97]
	s_mov_b32 m0, s14
	s_nop 0
	global_load_lds_dwordx4 v[20:21], off
	s_add_i32 s15, s69, 0x14000
	v_lshl_add_u64 v[20:21], s[4:5], 0, v[98:99]
	s_mov_b32 m0, s15
	s_nop 0
	global_load_lds_dwordx4 v[20:21], off
	v_lshl_add_u64 v[20:21], s[0:1], 0, v[100:101]
	s_add_i32 s0, s69, 0x10400
	s_mov_b32 m0, s0
	s_nop 0
	global_load_lds_dwordx4 v[20:21], off
	v_lshl_add_u64 v[20:21], s[4:5], 0, v[102:103]
	s_add_i32 s0, s69, 0x14400
	s_mov_b32 m0, s0
	s_nop 0
	global_load_lds_dwordx4 v[20:21], off

.LBB0_425:
	s_andn2_b64 vcc, exec, s[4:5]
	s_cbranch_vccnz .LBB0_427
	s_add_i32 s0, s82, s85
	s_add_i32 s4, s0, 3
	s_lshr_b32 s5, s4, 2
	s_and_b32 s4, s4, 3
	s_cmp_lt_u32 s1, s68
	s_cselect_b32 s5, s80, s5
	s_cselect_b32 s1, s1, s4
	s_lshl_b32 s4, s5, 8
	s_lshl_b32 s1, s1, 6
	s_add_i32 s46, s4, s1
	s_add_i32 s1, s78, 0x18000
	s_and_b32 s1, s1, 0x18000
	s_lshl_b64 s[4:5], s[46:47], 8
	s_add_i32 s1, s69, s1
	s_add_u32 s14, s59, s4
	s_addc_u32 s15, s65, s5
	s_add_u32 s4, s66, s4
	s_addc_u32 s5, s67, s5
	v_lshl_add_u64 v[48:49], s[14:15], 0, v[96:97]
	s_mov_b32 m0, s1
	s_nop 0
	global_load_lds_dwordx4 v[48:49], off
	s_add_i32 s46, s1, 0x4000
	v_lshl_add_u64 v[48:49], s[4:5], 0, v[98:99]
	s_mov_b32 m0, s46
	s_nop 0
	global_load_lds_dwordx4 v[48:49], off
	v_lshl_add_u64 v[48:49], s[14:15], 0, v[100:101]
	s_add_i32 s14, s1, 0x400
	s_mov_b32 m0, s14
	s_nop 0
	global_load_lds_dwordx4 v[48:49], off
	v_lshl_add_u64 v[48:49], s[4:5], 0, v[102:103]
	s_addk_i32 s1, 0x4400
	s_mov_b32 m0, s1
	s_nop 0
	global_load_lds_dwordx4 v[48:49], off

.LBB0_435:
	v_max3_f32 v134, v92, v93, v94
	s_nop 5
	v_max_f32_e32 v135, v83, v83
	v_max3_f32 v134, v134, v95, v88
	s_or_b64 s[4:5], s[52:53], s[4:5]
	v_max3_f32 v134, v134, v89, v90
	v_max3_f32 v134, v134, v91, v84
	v_max3_f32 v134, v134, v85, v86
	v_max3_f32 v134, v134, v87, v80
	v_max3_f32 v134, v134, v81, v82
	s_nop 0
	v_max_f32_e32 v134, v134, v134
	v_max_f32_e32 v134, v134, v135
	v_cndmask_b32_e64 v134, v106, v134, s[4:5]
	ds_swizzle_b32 v135, v134 offset:swizzle(SWAP,16)
	s_waitcnt lgkmcnt(0)
	v_max_f32_e32 v135, v135, v135
	v_max_f32_e32 v134, v134, v135
	ds_bpermute_b32 v135, v105, v134
	s_waitcnt lgkmcnt(0)
	v_max_f32_e32 v135, v135, v135
	v_max_f32_e32 v134, v134, v135
	v_mul_f32_e32 v134, 0x3e0293ee, v134
	v_add_f32_e32 v135, 0x41000000, v108
	v_cmp_gt_f32_e32 vcc, v134, v135
	s_cbranch_vccz .LBB0_413
	v_max_f32_e32 v134, v134, v134
	v_max_f32_e32 v135, v108, v108
	v_max_f32_e32 v134, v135, v134
	v_sub_f32_e32 v108, v108, v134
	v_exp_f32_e32 v108, v108
	s_nop 0
	v_pk_mul_f32 v[42:43], v[42:43], v[108:109] op_sel_hi:[1,0]
	v_pk_mul_f32 v[40:41], v[40:41], v[108:109] op_sel_hi:[1,0]
	v_pk_mul_f32 v[46:47], v[46:47], v[108:109] op_sel_hi:[1,0]
	v_pk_mul_f32 v[44:45], v[44:45], v[108:109] op_sel_hi:[1,0]
	v_pk_mul_f32 v[38:39], v[38:39], v[108:109] op_sel_hi:[1,0]
	v_pk_mul_f32 v[36:37], v[36:37], v[108:109] op_sel_hi:[1,0]
	v_pk_mul_f32 v[34:35], v[34:35], v[108:109] op_sel_hi:[1,0]
	v_pk_mul_f32 v[32:33], v[32:33], v[108:109] op_sel_hi:[1,0]
	v_pk_mul_f32 v[30:31], v[30:31], v[108:109] op_sel_hi:[1,0]
	v_pk_mul_f32 v[28:29], v[28:29], v[108:109] op_sel_hi:[1,0]
	v_pk_mul_f32 v[26:27], v[26:27], v[108:109] op_sel_hi:[1,0]
	v_pk_mul_f32 v[24:25], v[24:25], v[108:109] op_sel_hi:[1,0]
	v_pk_mul_f32 v[22:23], v[22:23], v[108:109] op_sel_hi:[1,0]
	v_pk_mul_f32 v[20:21], v[20:21], v[108:109] op_sel_hi:[1,0]
	v_pk_mul_f32 v[18:19], v[18:19], v[108:109] op_sel_hi:[1,0]
	v_pk_mul_f32 v[16:17], v[16:17], v[108:109] op_sel_hi:[1,0]
	v_mul_f32_e32 v124, v124, v108
	v_mov_b32_e32 v108, v134
	s_branch .LBB0_413
